# MoBA attention loop: loop-invariant LDS read address terms hoisted to the item preheader (2 fewer VALU per step on the post-barrier path)
# baseline (speedup 1.0000x reference)
; template <int DQ, int TYPE>
; __device__ __forceinline__ void attn_item(PP p, int layer, int b, int h, int qt, char* lds, const int tid_, unsigned* next_ctr, volatile XLAS unsigned* slot) {
;     ...
;     f32x16 O[4];
; #pragma unroll
;     for (int md = 0; md < 4; ++md)
; #pragma unroll
;         for (int i = 0; i < 16; ++i) O[md][i] = 0.f;
;     float m_run = -1e30f, l_run = 0.f;
;     if (TYPE == 2 && kh == 0) { m_run = p->sinks[layer * 8 + h] * LOG2E; l_run = (hh == 0) ? 1.f : 0.f; }
;     constexpr int GK = (DQ == 192) ? 3 : 4, NG = NKS / GK;
;     A_LSTORE(A, 0); __syncthreads();
;     if (kh == 0) __builtin_amdgcn_s_setprio(2);
; #pragma unroll 1
;     for (int j = j_lo; j <= j_hi; ++j) {
.LBB0_637:
	s_waitcnt vmcnt(0)
	s_ashr_i32 s54, s88, 8
	s_lshl_b32 s58, s54, 5
	v_or_b32_e32 v2, s58, v154
	v_mov_b32_e32 v18, v1
	v_mov_b32_e32 v19, v1
	v_mov_b32_e32 v32, v1
	v_mov_b32_e32 v33, v1
	v_mul_lo_u32 v162, v2, s84
	s_lshl_b32 s12, s49, 1
	v_mov_b32_e32 v20, v1
	v_mov_b32_e32 v21, v1
	v_mov_b32_e32 v22, v1
	v_mov_b32_e32 v23, v1
	v_mov_b32_e32 v24, v1
	v_mov_b32_e32 v25, v1
	v_mov_b32_e32 v26, v1
	v_mov_b32_e32 v27, v1
	v_mov_b32_e32 v28, v1
	v_mov_b32_e32 v29, v1
	v_mov_b32_e32 v30, v1
	v_mov_b32_e32 v31, v1
	v_mov_b64_e32 v[2:3], v[18:19]
	v_mov_b64_e32 v[64:65], v[32:33]
	v_mov_b64_e32 v[48:49], v[32:33]
	v_mul_u32_u24_e32 v161, 17, v185
	s_lshl_b32 s57, s80, 1
	s_or_b32 s59, s95, 31
	v_and_b32_e32 v244, 7, v154
	v_lshrrev_b32_e32 v245, 3, v154
	v_mad_u32_u24 v244, v244, 18, v245
	v_mul_u32_u24_e32 v163, 0x88, v244
	v_lshlrev_b32_e32 v147, 2, v155
	s_sub_i32 s60, 64, s12
	s_mov_b32 s61, 0
	v_mov_b32_e32 v164, 0
	v_mov_b32_e32 v176, 0xf149f2ca
	s_mov_b32 s62, s58
	v_mov_b64_e32 v[4:5], v[20:21]
	v_mov_b64_e32 v[6:7], v[22:23]
	v_mov_b64_e32 v[8:9], v[24:25]
	v_mov_b64_e32 v[10:11], v[26:27]
	v_mov_b64_e32 v[12:13], v[28:29]
	v_mov_b64_e32 v[14:15], v[30:31]
	v_mov_b64_e32 v[16:17], v[32:33]
	v_mov_b64_e32 v[62:63], v[30:31]
	v_mov_b64_e32 v[60:61], v[28:29]
	v_mov_b64_e32 v[58:59], v[26:27]
	v_mov_b64_e32 v[56:57], v[24:25]
	v_mov_b64_e32 v[54:55], v[22:23]
	v_mov_b64_e32 v[52:53], v[20:21]
	v_mov_b64_e32 v[50:51], v[18:19]
	v_mov_b64_e32 v[46:47], v[30:31]
	v_mov_b64_e32 v[44:45], v[28:29]
	v_mov_b64_e32 v[42:43], v[26:27]
	v_mov_b64_e32 v[40:41], v[24:25]
	v_mov_b64_e32 v[38:39], v[22:23]
	v_mov_b64_e32 v[36:37], v[20:21]
	v_mov_b64_e32 v[34:35], v[18:19]
	v_lshl_add_u32 v238, v153, 1, v162
	v_lshl_add_u32 v239, v147, 1, v163
	s_mov_b32 s98, 0x10000
	s_mov_b32 s99, 0
	v_lshlrev_b64 v[232:233], 10, v[166:167]
	v_lshlrev_b64 v[234:235], 10, v[168:169]
	v_lshlrev_b64 v[236:237], 10, v[170:171]
	v_lshl_add_u64 v[232:233], v[148:149], 0, v[232:233]
	v_lshl_add_u64 v[234:235], v[148:149], 0, v[234:235]
	v_lshl_add_u64 v[236:237], v[150:151], 0, v[236:237]
	v_lshl_add_u64 v[232:233], s[98:99], 0, v[232:233]
	v_lshl_add_u64 v[234:235], s[98:99], 0, v[234:235]
	v_lshl_add_u64 v[236:237], s[98:99], 0, v[236:237]
	s_cmp_le_u32 s61, s57
	s_cselect_b64 s[12:13], -1, 0
	s_cmp_gt_u32 s61, s57
	s_cbranch_scc1 .LBB0_640
	s_branch .LBB0_639

; template <int DQ, int TYPE>
; __device__ __forceinline__ void attn_item(PP p, int layer, int b, int h, int qt, char* lds, const int tid_, unsigned* next_ctr, volatile XLAS unsigned* slot) {
;     ...
;             const bf16_t* Ks = (const bf16_t*)(lds + buf * STAGE); const bf16_t* Vt = (const bf16_t*)(lds + buf * STAGE + KBYTES);
;             f32x16 sacc;
; #pragma unroll
;             for (int i = 0; i < 16; ++i) sacc[i] = 0.f;
;             const bf16_t* kb_ = Ks + (32 * kh + r) * KLD + 8 * hh;
;             bf16x8 kf[2][GK];
; #pragma unroll
;             for (int i = 0; i < GK; ++i) kf[0][i] = *(const bf16x8*)(kb_ + 16 * i);
; #pragma unroll
;             for (int g = 0; g < NG; ++g) {
;                 if (g + 1 < NG) {
; #pragma unroll
;                     for (int i = 0; i < GK; ++i) kf[(g + 1) & 1][i] = *(const bf16x8*)(kb_ + 16 * ((g + 1) * GK + i));
;                 }
;                 __builtin_amdgcn_sched_barrier(0);
; #pragma unroll
;                 for (int i = 0; i < GK; ++i) sacc = __builtin_amdgcn_mfma_f32_32x32x16_bf16(kf[g & 1][i], qf[g * GK + i], sacc, 0, 0, 0);
;                 __builtin_amdgcn_sched_barrier(0);
;             }
;             const bf16_t* vb0 = Vt + r * VLD + 32 * kh + 4 * hh;
;             u32x2 vf[2][4][2];
; #pragma unroll
;             for (int md = 0; md < 4; ++md) { vf[0][md][0] = *(const u32x2*)(vb0 + md * 32 * VLD); vf[0][md][1] = *(const u32x2*)(vb0 + md * 32 * VLD + 8); }
;             if (mode != 0) {
;                 const bool selbit = (qmask >> (j >> 2)) & 1u;
; #pragma unroll
;                 for (int i = 0; i < 16; ++i) {
;                     const int kpos = kbase_pos + 8 * (i >> 2) + 4 * hh + (i & 3);
;                     const int dd = qpos - kpos;
;                     bool ok;
;                     if (mode == 1) ok = dd >= 0; else if (mode == 2) ok = (dd >= 0 && dd < 128); else ok = selbit;
;                     if (!ok) sacc[i] = -INFINITY;
;                 }
;             }
.LBB0_640:
	s_and_b32 s63, s61, 1
	s_lshr_b32 s64, s61, 2
	s_cmp_ge_u32 s64, s94
	s_cselect_b64 s[14:15], -1, 0
	s_cmp_lt_u32 s61, s57
	s_cselect_b64 s[16:17], -1, 0
	s_cmp_ge_u32 s61, s57
	s_cselect_b64 s[50:51], -1, 0
	s_and_b64 s[50:51], s[14:15], s[50:51]
	s_cmp_gt_i32 s62, s59
	s_cselect_b64 s[66:67], -1, 0
	s_and_b64 s[66:67], s[50:51], s[66:67]
	s_and_b64 vcc, exec, s[66:67]
	s_cbranch_vccnz .LBB0_646
	s_and_b64 s[14:15], s[14:15], s[16:17]
	s_mul_i32 s16, s63, 0x8f70
	s_add_i32 s16, s16, 16
	v_add_u32_e32 v70, s16, v238
	ds_read_b128 v[66:69], v70
	ds_read_b128 v[130:133], v70 offset:32
	ds_read_b128 v[134:137], v70 offset:64
	ds_read_b128 v[138:141], v70 offset:96
	ds_read_b128 v[142:145], v70 offset:128
	ds_read_b128 v[172:175], v70 offset:160
	ds_read_b128 v[190:193], v70 offset:192
	ds_read_b128 v[194:197], v70 offset:224
	s_waitcnt lgkmcnt(7)
	v_mfma_f32_32x32x16_bf16 v[66:81], v[66:69], v[90:93], 0
	s_waitcnt lgkmcnt(6)
	v_mfma_f32_32x32x16_bf16 v[66:81], v[130:133], v[94:97], v[66:81]
	s_waitcnt lgkmcnt(5)
	v_mfma_f32_32x32x16_bf16 v[66:81], v[134:137], v[98:101], v[66:81]
	s_waitcnt lgkmcnt(4)
	v_mfma_f32_32x32x16_bf16 v[66:81], v[138:141], v[102:105], v[66:81]
	s_waitcnt lgkmcnt(3)
	v_mfma_f32_32x32x16_bf16 v[66:81], v[142:145], v[110:113], v[66:81]
	s_lshl_b32 s17, s58, 1
	s_add_i32 s17, s17, s16
	v_add_u32_e32 v130, s17, v239
	s_and_b64 vcc, exec, s[14:15]
	s_waitcnt lgkmcnt(2)
	v_mfma_f32_32x32x16_bf16 v[66:81], v[172:175], v[114:117], v[66:81]
	v_add_u32_e32 v173, 0x4000, v130
	v_add_u32_e32 v175, 0x4120, v130
	v_add_u32_e32 v174, 0x4240, v130
	v_add_u32_e32 v172, 0x4360, v130
	ds_read2_b64 v[142:145], v173 offset0:128 offset1:130
	ds_read2_b64 v[138:141], v175 offset0:160 offset1:162
	ds_read2_b64 v[134:137], v174 offset0:192 offset1:194
	s_waitcnt lgkmcnt(4)
	v_mfma_f32_32x32x16_bf16 v[66:81], v[190:193], v[122:125], v[66:81]
	ds_read2_b64 v[130:133], v172 offset0:224 offset1:226
	s_waitcnt lgkmcnt(4)
	v_mfma_f32_32x32x16_bf16 v[66:81], v[194:197], v[126:129], v[66:81]
	s_cbranch_vccnz .LBB0_643
	s_cmp_eq_u64 s[50:51], 0
	s_cbranch_scc0 .Lmoba_mask_slow
	v_lshrrev_b32_e32 v152, s64, v157
	v_and_b32_e32 v152, 1, v152
	v_cmp_eq_u32_e32 vcc, 1, v152
	s_nop 5
	v_cndmask_b32_e32 v66, v225, v66, vcc
	v_cndmask_b32_e32 v67, v225, v67, vcc
	v_cndmask_b32_e32 v68, v225, v68, vcc
	v_cndmask_b32_e32 v69, v225, v69, vcc
	v_cndmask_b32_e32 v70, v225, v70, vcc
	v_cndmask_b32_e32 v71, v225, v71, vcc
	v_cndmask_b32_e32 v72, v225, v72, vcc
	v_cndmask_b32_e32 v73, v225, v73, vcc
	v_cndmask_b32_e32 v74, v225, v74, vcc
	v_cndmask_b32_e32 v75, v225, v75, vcc
	v_cndmask_b32_e32 v76, v225, v76, vcc
	v_cndmask_b32_e32 v77, v225, v77, vcc
	v_cndmask_b32_e32 v78, v225, v78, vcc
	v_cndmask_b32_e32 v79, v225, v79, vcc
	v_cndmask_b32_e32 v80, v225, v80, vcc
	v_cndmask_b32_e32 v81, v225, v81, vcc
	s_branch .Lmoba_after_nop
